# as combo4 plus nt on read-once x/Y1 row loads in the two norm/residual phases P1 and P4
# baseline (speedup 1.0000x reference)
.LBB0_113:
	s_ashr_i32 s15, s14, 31
	s_add_i32 s0, s14, 1
	s_ashr_i32 s20, s17, 11
	s_add_i32 s4, s14, 2
	s_add_i32 s8, s14, 3
	s_lshl_b64 s[18:19], s[14:15], 12
	s_ashr_i32 s1, s0, 31
	s_mul_i32 s20, s20, 9
	s_ashr_i32 s5, s4, 31
	s_ashr_i32 s9, s8, 31
	v_lshl_add_u64 v[0:1], v[68:69], 0, s[18:19]
	s_lshl_b64 s[18:19], s[0:1], 12
	s_ashr_i32 s21, s20, 31
	s_lshl_b64 s[26:27], s[4:5], 12
	s_lshl_b64 s[28:29], s[8:9], 12
	v_lshl_add_u64 v[76:77], v[68:69], 0, s[18:19]
	s_lshl_b64 s[18:19], s[20:21], 12
	global_load_dwordx4 v[64:67], v[72:73], off
	global_load_dwordx4 v[36:39], v[0:1], off nt
	global_load_dwordx4 v[20:23], v[0:1], off offset:1024 nt
	global_load_dwordx4 v[16:19], v[0:1], off offset:2048 nt
	s_nop 0
	global_load_dwordx4 v[0:3], v[0:1], off offset:3072 nt
	s_add_u32 s18, s2, s18
	s_addc_u32 s19, s3, s19
	s_add_u32 s20, s18, 0x1000
	v_lshl_add_u64 v[78:79], v[68:69], 0, s[26:27]
	v_lshl_add_u64 v[80:81], v[68:69], 0, s[28:29]
	global_load_dwordx4 v[52:55], v[76:77], off nt
	global_load_dwordx4 v[48:51], v[76:77], off offset:1024 nt
	global_load_dwordx4 v[56:59], v[78:79], off nt
	global_load_dwordx4 v[44:47], v[78:79], off offset:1024 nt
	global_load_dwordx4 v[60:63], v[80:81], off nt
	global_load_dwordx4 v[40:43], v[80:81], off offset:1024 nt
	global_load_dwordx4 v[24:27], v[76:77], off offset:2048 nt
	global_load_dwordx4 v[4:7], v[76:77], off offset:3072 nt
	global_load_dwordx4 v[28:31], v[78:79], off offset:2048 nt
	global_load_dwordx4 v[8:11], v[78:79], off offset:3072 nt
	global_load_dwordx4 v[32:35], v[80:81], off offset:2048 nt
	global_load_dwordx4 v[12:15], v[80:81], off offset:3072 nt
	s_addc_u32 s21, s19, 0
	global_load_dwordx4 v[94:97], v90, s[20:21]
	global_load_dwordx4 v[98:101], v90, s[18:19]
	s_lshl_b64 s[8:9], s[8:9], 11
	s_lshl_b64 s[0:1], s[0:1], 11
	s_lshl_b64 s[4:5], s[4:5], 11
	v_lshl_add_u64 v[82:83], v[70:71], 0, s[8:9]
	v_lshl_add_u64 v[78:79], v[70:71], 0, s[0:1]
	v_lshl_add_u64 v[80:81], v[70:71], 0, s[4:5]
	s_lshl_b64 s[26:27], s[14:15], 11
	v_lshl_add_u64 v[76:77], v[70:71], 0, s[26:27]
	s_add_i32 s14, s14, s23
	s_waitcnt vmcnt(13)
	v_pk_mul_f32 v[116:117], v[52:53], v[52:53]
	s_waitcnt vmcnt(12)
	v_pk_mul_f32 v[118:119], v[50:51], v[50:51]
	v_pk_mul_f32 v[102:103], v[38:39], v[38:39]
	v_pk_mul_f32 v[104:105], v[36:37], v[36:37]
	v_pk_mul_f32 v[106:107], v[22:23], v[22:23]
	v_pk_mul_f32 v[108:109], v[20:21], v[20:21]
	v_mul_f32_e32 v110, v17, v17
	v_mul_f32_e32 v112, v19, v19
	v_pk_mov_b32 v[114:115], v[104:105], v[102:103] op_sel:[1,0]
	v_mov_b32_e32 v105, v103
	v_pk_mov_b32 v[102:103], v[108:109], v[106:107] op_sel:[1,0]
	v_mov_b32_e32 v109, v107
	v_pk_mul_f32 v[106:107], v[54:55], v[54:55]
	v_pk_mul_f32 v[120:121], v[48:49], v[48:49]
	v_mul_f32_e32 v139, v2, v2
	v_mul_f32_e32 v141, v3, v3
	s_waitcnt vmcnt(11)
	v_pk_mul_f32 v[122:123], v[58:59], v[58:59]
	v_pk_mul_f32 v[124:125], v[56:57], v[56:57]
	s_waitcnt vmcnt(10)
	v_pk_mul_f32 v[126:127], v[46:47], v[46:47]
	v_pk_mul_f32 v[128:129], v[44:45], v[44:45]
	s_waitcnt vmcnt(9)
	v_pk_mul_f32 v[130:131], v[62:63], v[62:63]
	v_pk_mul_f32 v[132:133], v[60:61], v[60:61]
	s_waitcnt vmcnt(8)
	v_pk_mul_f32 v[134:135], v[42:43], v[42:43]
	v_pk_mul_f32 v[136:137], v[40:41], v[40:41]
	v_pk_fma_f32 v[110:111], v[16:17], v[16:17], v[110:111] op_sel_hi:[1,1,0]
	v_pk_fma_f32 v[112:113], v[18:19], v[18:19], v[112:113] op_sel_hi:[1,1,0]
	v_pk_add_f32 v[102:103], v[102:103], v[108:109]
	v_pk_mov_b32 v[108:109], v[116:117], v[106:107] op_sel:[1,0]
	v_mov_b32_e32 v117, v107
	v_pk_mov_b32 v[106:107], v[120:121], v[118:119] op_sel:[1,0]
	v_mov_b32_e32 v121, v119
	s_waitcnt vmcnt(7)
	v_mul_f32_e32 v140, v25, v25
	v_mul_f32_e32 v142, v27, v27
	v_pk_add_f32 v[104:105], v[114:115], v[104:105]
	v_pk_mov_b32 v[114:115], v[124:125], v[122:123] op_sel:[1,0]
	v_mov_b32_e32 v125, v123
	v_pk_mov_b32 v[118:119], v[128:129], v[126:127] op_sel:[1,0]
	v_mov_b32_e32 v129, v127
	v_pk_mov_b32 v[122:123], v[132:133], v[130:131] op_sel:[1,0]
	v_mov_b32_e32 v133, v131
	v_pk_mov_b32 v[126:127], v[136:137], v[134:135] op_sel:[1,0]
	v_mov_b32_e32 v137, v135
	v_mov_b32_e32 v111, v139
	v_mov_b32_e32 v113, v141
	v_pk_add_f32 v[108:109], v[108:109], v[116:117]
	v_pk_add_f32 v[106:107], v[106:107], v[120:121]
	v_mul_f32_e32 v149, v0, v0
	v_mul_f32_e32 v151, v1, v1
	s_waitcnt vmcnt(6)
	v_mul_f32_e32 v152, v6, v6
	v_mul_f32_e32 v153, v7, v7
	s_waitcnt vmcnt(5)
	v_mul_f32_e32 v144, v29, v29
	v_mul_f32_e32 v146, v31, v31
	s_waitcnt vmcnt(3)
	v_mul_f32_e32 v148, v33, v33
	v_mul_f32_e32 v150, v35, v35
	v_mul_f32_e32 v158, v4, v4
	v_mul_f32_e32 v159, v5, v5
	v_pk_fma_f32 v[130:131], v[24:25], v[24:25], v[140:141] op_sel_hi:[1,1,0]
	v_pk_fma_f32 v[134:135], v[26:27], v[26:27], v[142:143] op_sel_hi:[1,1,0]
	v_pk_add_f32 v[110:111], v[110:111], v[112:113]
	v_pk_add_f32 v[112:113], v[114:115], v[124:125]
	v_pk_add_f32 v[114:115], v[118:119], v[128:129]
	v_pk_add_f32 v[116:117], v[122:123], v[132:133]
	v_pk_add_f32 v[118:119], v[126:127], v[136:137]
	v_pk_add_f32 v[104:105], v[104:105], v[104:105] op_sel:[0,1] op_sel_hi:[1,0]
	v_pk_add_f32 v[102:103], v[102:103], v[102:103] op_sel:[0,1] op_sel_hi:[1,0]
	v_pk_add_f32 v[108:109], v[108:109], v[108:109] op_sel:[0,1] op_sel_hi:[1,0]
	v_pk_add_f32 v[106:107], v[106:107], v[106:107] op_sel:[0,1] op_sel_hi:[1,0]
	v_mul_f32_e32 v154, v10, v10
	v_mul_f32_e32 v155, v11, v11
	s_waitcnt vmcnt(2)
	v_mul_f32_e32 v156, v14, v14
	v_mul_f32_e32 v157, v15, v15
	v_mul_f32_e32 v160, v8, v8
	v_mul_f32_e32 v161, v9, v9
	v_mul_f32_e32 v162, v12, v12
	v_mul_f32_e32 v163, v13, v13
	v_pk_fma_f32 v[140:141], v[28:29], v[28:29], v[144:145] op_sel_hi:[1,1,0]
	v_pk_fma_f32 v[142:143], v[30:31], v[30:31], v[146:147] op_sel_hi:[1,1,0]
	v_pk_fma_f32 v[144:145], v[32:33], v[32:33], v[148:149] op_sel_hi:[1,1,0]
	v_pk_fma_f32 v[146:147], v[34:35], v[34:35], v[150:151] op_sel_hi:[1,1,0]
	v_mov_b32_e32 v131, v152
	v_mov_b32_e32 v135, v153
	v_mov_b32_e32 v105, v149
	v_mov_b32_e32 v103, v151
	v_pk_add_f32 v[112:113], v[112:113], v[112:113] op_sel:[0,1] op_sel_hi:[1,0]
	v_pk_add_f32 v[114:115], v[114:115], v[114:115] op_sel:[0,1] op_sel_hi:[1,0]
	v_pk_add_f32 v[116:117], v[116:117], v[116:117] op_sel:[0,1] op_sel_hi:[1,0]
	v_pk_add_f32 v[118:119], v[118:119], v[118:119] op_sel:[0,1] op_sel_hi:[1,0]
	s_waitcnt vmcnt(1)
	v_pk_add_f32 v[96:97], v[96:97], 1.0 op_sel_hi:[1,0]
	v_mov_b32_e32 v109, v158
	v_mov_b32_e32 v107, v159
	v_mov_b32_e32 v141, v154
	v_mov_b32_e32 v143, v155
	v_mov_b32_e32 v145, v156
	v_mov_b32_e32 v147, v157
	v_pk_add_f32 v[120:121], v[130:131], v[134:135]
	v_pk_add_f32 v[94:95], v[94:95], 1.0 op_sel_hi:[1,0]
	v_pk_add_f32 v[102:103], v[104:105], v[102:103]
	v_mov_b32_e32 v113, v160
	v_mov_b32_e32 v115, v161
	v_mov_b32_e32 v117, v162
	v_mov_b32_e32 v119, v163
	v_pk_mul_f32 v[66:67], v[66:67], v[96:97]
	v_pk_add_f32 v[96:97], v[108:109], v[106:107]
	v_pk_add_f32 v[122:123], v[140:141], v[142:143]
	v_pk_add_f32 v[124:125], v[144:145], v[146:147]
	v_pk_mul_f32 v[64:65], v[64:65], v[94:95]
	v_pk_add_f32 v[94:95], v[102:103], v[110:111]
	v_pk_add_f32 v[102:103], v[112:113], v[114:115]
	v_pk_add_f32 v[104:105], v[116:117], v[118:119]
	v_pk_add_f32 v[96:97], v[96:97], v[120:121]
	v_pk_add_f32 v[102:103], v[102:103], v[122:123]
	v_pk_add_f32 v[104:105], v[104:105], v[124:125]
	v_mov_b32_e32 v107, v94
	v_mov_b32_e32 v106, v96
	v_mov_b32_e32 v94, v97
	v_mov_b32_e32 v96, v104
	v_mov_b32_e32 v97, v102
	v_mov_b32_e32 v102, v105
	v_pk_add_f32 v[94:95], v[106:107], v[94:95]
	v_pk_add_f32 v[96:97], v[96:97], v[102:103]
	ds_bpermute_b32 v103, v84, v95
	ds_bpermute_b32 v102, v84, v94
	ds_bpermute_b32 v105, v84, v97
	ds_bpermute_b32 v104, v84, v96
	s_waitcnt lgkmcnt(2)
	v_pk_add_f32 v[94:95], v[94:95], v[102:103]
	ds_bpermute_b32 v103, v85, v95
	s_waitcnt lgkmcnt(1)
	v_pk_add_f32 v[96:97], v[96:97], v[104:105]
	ds_bpermute_b32 v102, v85, v94
	ds_bpermute_b32 v105, v85, v97
	ds_bpermute_b32 v104, v85, v96
	s_waitcnt lgkmcnt(2)
	v_pk_add_f32 v[94:95], v[94:95], v[102:103]
	ds_bpermute_b32 v103, v86, v95
	s_waitcnt lgkmcnt(1)
	v_pk_add_f32 v[96:97], v[96:97], v[104:105]
	ds_bpermute_b32 v102, v86, v94
	ds_bpermute_b32 v105, v86, v97
	ds_bpermute_b32 v104, v86, v96
	s_waitcnt lgkmcnt(2)
	v_pk_add_f32 v[94:95], v[94:95], v[102:103]
	ds_bpermute_b32 v103, v87, v95
	s_waitcnt lgkmcnt(1)
	v_pk_add_f32 v[96:97], v[96:97], v[104:105]
	ds_bpermute_b32 v102, v87, v94
	ds_bpermute_b32 v105, v87, v97
	ds_bpermute_b32 v104, v87, v96
	s_waitcnt lgkmcnt(2)
	v_pk_add_f32 v[94:95], v[94:95], v[102:103]
	ds_bpermute_b32 v103, v88, v95
	s_waitcnt lgkmcnt(1)
	v_pk_add_f32 v[96:97], v[96:97], v[104:105]
	ds_bpermute_b32 v102, v88, v94
	ds_bpermute_b32 v105, v88, v97
	ds_bpermute_b32 v104, v88, v96
	s_waitcnt lgkmcnt(2)
	v_pk_add_f32 v[94:95], v[94:95], v[102:103]
	ds_bpermute_b32 v103, v89, v95
	s_waitcnt lgkmcnt(1)
	v_pk_add_f32 v[96:97], v[96:97], v[104:105]
	ds_bpermute_b32 v102, v89, v94
	ds_bpermute_b32 v105, v89, v97
	ds_bpermute_b32 v104, v89, v96
	s_waitcnt lgkmcnt(2)
	v_pk_add_f32 v[94:95], v[94:95], v[102:103]
	s_nop 0
	v_pk_fma_f32 v[94:95], v[94:95], s[16:17], v[74:75] op_sel_hi:[1,0,0]
	s_waitcnt lgkmcnt(0)
	v_pk_add_f32 v[96:97], v[96:97], v[104:105]
	v_mul_f32_e32 v103, 0x4b800000, v95
	v_pk_fma_f32 v[96:97], v[96:97], s[16:17], v[74:75] op_sel_hi:[1,0,0]
	v_cmp_gt_f32_e64 s[8:9], s24, v95
	v_mul_f32_e32 v102, 0x4b800000, v94
	v_cmp_gt_f32_e32 vcc, s24, v94
	v_mul_f32_e32 v104, 0x4b800000, v96
	v_cmp_gt_f32_e64 s[0:1], s24, v96
	v_mul_f32_e32 v105, 0x4b800000, v97
	v_cmp_gt_f32_e64 s[4:5], s24, v97
	v_cndmask_b32_e64 v95, v95, v103, s[8:9]
	v_cndmask_b32_e32 v94, v94, v102, vcc
	v_cndmask_b32_e64 v97, v97, v105, s[4:5]
	v_cndmask_b32_e64 v96, v96, v104, s[0:1]
	v_rsq_f32_e32 v95, v95
	v_rsq_f32_e32 v102, v94
	v_rsq_f32_e32 v97, v97
	v_rsq_f32_e32 v103, v96
	v_mul_f32_e32 v94, 0x45800000, v95
	v_mul_f32_e32 v96, 0x45800000, v102
	v_mul_f32_e32 v104, 0x45800000, v97
	v_mul_f32_e32 v105, 0x45800000, v103
	v_cndmask_b32_e64 v94, v95, v94, s[8:9]
	v_cndmask_b32_e32 v96, v102, v96, vcc
	v_cndmask_b32_e64 v102, v97, v104, s[4:5]
	v_cndmask_b32_e64 v104, v103, v105, s[0:1]
	v_pk_mul_f32 v[36:37], v[36:37], v[94:95] op_sel_hi:[1,0]
	v_pk_mul_f32 v[38:39], v[38:39], v[94:95] op_sel_hi:[1,0]
	v_pk_mul_f32 v[52:53], v[52:53], v[96:97] op_sel_hi:[1,0]
	v_pk_mul_f32 v[54:55], v[54:55], v[96:97] op_sel_hi:[1,0]
	v_pk_mul_f32 v[56:57], v[56:57], v[102:103] op_sel_hi:[1,0]
	v_pk_mul_f32 v[58:59], v[58:59], v[102:103] op_sel_hi:[1,0]
	v_pk_mul_f32 v[60:61], v[60:61], v[104:105] op_sel_hi:[1,0]
	v_pk_mul_f32 v[62:63], v[62:63], v[104:105] op_sel_hi:[1,0]
	s_waitcnt vmcnt(0)
	v_pk_fma_f32 v[38:39], v[38:39], v[66:67], v[100:101]
	v_pk_fma_f32 v[36:37], v[36:37], v[64:65], v[98:99]
	v_pk_fma_f32 v[54:55], v[54:55], v[66:67], v[100:101]
	v_pk_fma_f32 v[58:59], v[66:67], v[58:59], v[100:101]
	v_pk_fma_f32 v[62:63], v[66:67], v[62:63], v[100:101]
	v_pk_fma_f32 v[52:53], v[52:53], v[64:65], v[98:99]
	v_pk_fma_f32 v[56:57], v[64:65], v[56:57], v[98:99]
	v_pk_fma_f32 v[60:61], v[64:65], v[60:61], v[98:99]
	v_cvt_pk_bf16_f32 v36, v36, v37
	v_cvt_pk_bf16_f32 v37, v38, v39
	v_cvt_pk_bf16_f32 v38, v52, v53
	v_cvt_pk_bf16_f32 v39, v54, v55
	v_cvt_pk_bf16_f32 v52, v56, v57
	v_cvt_pk_bf16_f32 v53, v58, v59
	v_cvt_pk_bf16_f32 v54, v60, v61
	v_cvt_pk_bf16_f32 v55, v62, v63
	global_store_dwordx2 v[76:77], v[36:37], off
	global_store_dwordx2 v[78:79], v[38:39], off
	global_store_dwordx2 v[80:81], v[52:53], off
	global_store_dwordx2 v[82:83], v[54:55], off
	global_load_dwordx4 v[36:39], v91, s[20:21]
	s_nop 0
	global_load_dwordx4 v[52:55], v[72:73], off offset:1024
	global_load_dwordx4 v[56:59], v90, s[18:19] offset:1024
	v_pk_mul_f32 v[20:21], v[20:21], v[94:95] op_sel_hi:[1,0]
	v_pk_mul_f32 v[22:23], v[22:23], v[94:95] op_sel_hi:[1,0]
	v_pk_mul_f32 v[48:49], v[48:49], v[96:97] op_sel_hi:[1,0]
	v_pk_mul_f32 v[50:51], v[50:51], v[96:97] op_sel_hi:[1,0]
	v_pk_mul_f32 v[44:45], v[44:45], v[102:103] op_sel_hi:[1,0]
	v_pk_mul_f32 v[46:47], v[46:47], v[102:103] op_sel_hi:[1,0]
	v_pk_mul_f32 v[40:41], v[40:41], v[104:105] op_sel_hi:[1,0]
	v_pk_mul_f32 v[42:43], v[42:43], v[104:105] op_sel_hi:[1,0]
	v_pk_mul_f32 v[16:17], v[16:17], v[94:95] op_sel_hi:[1,0]
	v_pk_mul_f32 v[18:19], v[18:19], v[94:95] op_sel_hi:[1,0]
	v_pk_mul_f32 v[24:25], v[24:25], v[96:97] op_sel_hi:[1,0]
	v_pk_mul_f32 v[26:27], v[26:27], v[96:97] op_sel_hi:[1,0]
	v_pk_mul_f32 v[28:29], v[28:29], v[102:103] op_sel_hi:[1,0]
	v_pk_mul_f32 v[30:31], v[30:31], v[102:103] op_sel_hi:[1,0]
	v_pk_mul_f32 v[32:33], v[32:33], v[104:105] op_sel_hi:[1,0]
	v_pk_mul_f32 v[34:35], v[34:35], v[104:105] op_sel_hi:[1,0]
	v_pk_mul_f32 v[0:1], v[0:1], v[94:95] op_sel_hi:[1,0]
	v_pk_mul_f32 v[2:3], v[2:3], v[94:95] op_sel_hi:[1,0]
	s_add_i32 s17, s17, s22
	v_pk_mul_f32 v[4:5], v[4:5], v[96:97] op_sel_hi:[1,0]
	v_pk_mul_f32 v[6:7], v[6:7], v[96:97] op_sel_hi:[1,0]
	v_pk_mul_f32 v[8:9], v[8:9], v[102:103] op_sel_hi:[1,0]
	v_pk_mul_f32 v[10:11], v[10:11], v[102:103] op_sel_hi:[1,0]
	v_pk_mul_f32 v[12:13], v[12:13], v[104:105] op_sel_hi:[1,0]
	v_pk_mul_f32 v[14:15], v[14:15], v[104:105] op_sel_hi:[1,0]
	s_cmpk_lt_i32 s17, 0x4000
	s_waitcnt vmcnt(2)
	v_pk_add_f32 v[38:39], v[38:39], 1.0 op_sel_hi:[1,0]
	v_pk_add_f32 v[36:37], v[36:37], 1.0 op_sel_hi:[1,0]
	s_waitcnt vmcnt(1)
	v_pk_mul_f32 v[38:39], v[54:55], v[38:39]
	v_pk_mul_f32 v[36:37], v[52:53], v[36:37]
	s_waitcnt vmcnt(0)
	v_pk_fma_f32 v[22:23], v[22:23], v[38:39], v[58:59]
	v_pk_fma_f32 v[20:21], v[20:21], v[36:37], v[56:57]
	v_pk_fma_f32 v[50:51], v[50:51], v[38:39], v[58:59]
	v_pk_fma_f32 v[48:49], v[48:49], v[36:37], v[56:57]
	v_pk_fma_f32 v[46:47], v[46:47], v[38:39], v[58:59]
	v_pk_fma_f32 v[44:45], v[44:45], v[36:37], v[56:57]
	v_pk_fma_f32 v[38:39], v[38:39], v[42:43], v[58:59]
	v_pk_fma_f32 v[36:37], v[36:37], v[40:41], v[56:57]
	v_cvt_pk_bf16_f32 v20, v20, v21
	v_cvt_pk_bf16_f32 v21, v22, v23
	v_cvt_pk_bf16_f32 v22, v48, v49
	v_cvt_pk_bf16_f32 v23, v50, v51
	v_cvt_pk_bf16_f32 v40, v44, v45
	v_cvt_pk_bf16_f32 v41, v46, v47
	v_cvt_pk_bf16_f32 v36, v36, v37
	v_cvt_pk_bf16_f32 v37, v38, v39
	global_store_dwordx2 v[76:77], v[20:21], off offset:512
	global_store_dwordx2 v[78:79], v[22:23], off offset:512
	global_store_dwordx2 v[80:81], v[40:41], off offset:512
	global_store_dwordx2 v[82:83], v[36:37], off offset:512
	global_load_dwordx4 v[20:23], v92, s[20:21]
	s_nop 0
	global_load_dwordx4 v[36:39], v[72:73], off offset:2048
	global_load_dwordx4 v[40:43], v90, s[18:19] offset:2048
	s_waitcnt vmcnt(2)
	v_pk_add_f32 v[22:23], v[22:23], 1.0 op_sel_hi:[1,0]
	v_pk_add_f32 v[20:21], v[20:21], 1.0 op_sel_hi:[1,0]
	s_waitcnt vmcnt(1)
	v_pk_mul_f32 v[22:23], v[38:39], v[22:23]
	v_pk_mul_f32 v[20:21], v[36:37], v[20:21]
	s_waitcnt vmcnt(0)
	v_pk_fma_f32 v[18:19], v[18:19], v[22:23], v[42:43]
	v_pk_fma_f32 v[16:17], v[16:17], v[20:21], v[40:41]
	v_pk_fma_f32 v[26:27], v[26:27], v[22:23], v[42:43]
	v_pk_fma_f32 v[24:25], v[24:25], v[20:21], v[40:41]
	v_pk_fma_f32 v[30:31], v[30:31], v[22:23], v[42:43]
	v_pk_fma_f32 v[28:29], v[28:29], v[20:21], v[40:41]
	v_pk_fma_f32 v[22:23], v[34:35], v[22:23], v[42:43]
	v_pk_fma_f32 v[20:21], v[32:33], v[20:21], v[40:41]
	v_cvt_pk_bf16_f32 v16, v16, v17
	v_cvt_pk_bf16_f32 v17, v18, v19
	v_cvt_pk_bf16_f32 v18, v24, v25
	v_cvt_pk_bf16_f32 v19, v26, v27
	v_cvt_pk_bf16_f32 v24, v28, v29
	v_cvt_pk_bf16_f32 v25, v30, v31
	v_cvt_pk_bf16_f32 v20, v20, v21
	v_cvt_pk_bf16_f32 v21, v22, v23
	global_store_dwordx2 v[76:77], v[16:17], off offset:1024
	global_store_dwordx2 v[78:79], v[18:19], off offset:1024
	global_store_dwordx2 v[80:81], v[24:25], off offset:1024
	global_store_dwordx2 v[82:83], v[20:21], off offset:1024
	global_load_dwordx4 v[16:19], v93, s[20:21]
	s_nop 0
	global_load_dwordx4 v[20:23], v[72:73], off offset:3072
	global_load_dwordx4 v[24:27], v90, s[18:19] offset:3072
	s_waitcnt vmcnt(2)
	v_pk_add_f32 v[18:19], v[18:19], 1.0 op_sel_hi:[1,0]
	v_pk_add_f32 v[16:17], v[16:17], 1.0 op_sel_hi:[1,0]
	s_waitcnt vmcnt(1)
	v_pk_mul_f32 v[18:19], v[22:23], v[18:19]
	v_pk_mul_f32 v[16:17], v[20:21], v[16:17]
	s_waitcnt vmcnt(0)
	v_pk_fma_f32 v[2:3], v[2:3], v[18:19], v[26:27]
	v_pk_fma_f32 v[0:1], v[0:1], v[16:17], v[24:25]
	v_pk_fma_f32 v[6:7], v[6:7], v[18:19], v[26:27]
	v_pk_fma_f32 v[4:5], v[4:5], v[16:17], v[24:25]
	v_pk_fma_f32 v[10:11], v[10:11], v[18:19], v[26:27]
	v_pk_fma_f32 v[8:9], v[8:9], v[16:17], v[24:25]
	v_pk_fma_f32 v[14:15], v[14:15], v[18:19], v[26:27]
	v_pk_fma_f32 v[12:13], v[12:13], v[16:17], v[24:25]
	v_cvt_pk_bf16_f32 v0, v0, v1
	v_cvt_pk_bf16_f32 v1, v2, v3
	v_cvt_pk_bf16_f32 v2, v4, v5
	v_cvt_pk_bf16_f32 v3, v6, v7
	v_cvt_pk_bf16_f32 v4, v8, v9
	v_cvt_pk_bf16_f32 v5, v10, v11
	v_cvt_pk_bf16_f32 v6, v12, v13
	v_cvt_pk_bf16_f32 v7, v14, v15
	global_store_dwordx2 v[76:77], v[0:1], off offset:1536
	global_store_dwordx2 v[78:79], v[2:3], off offset:1536
	global_store_dwordx2 v[80:81], v[4:5], off offset:1536
	global_store_dwordx2 v[82:83], v[6:7], off offset:1536
	s_cbranch_scc1 .LBB0_113

.LBB0_316:
	s_ashr_i32 s18, s9, 12
	s_ashr_i32 s5, s4, 31
	s_add_i32 s0, s4, 1
	s_mul_i32 s18, s18, 9
	s_lshl_b64 s[14:15], s[4:5], 11
	s_lshl_b64 s[16:17], s[4:5], 12
	s_ashr_i32 s1, s0, 31
	s_ashr_i32 s19, s18, 31
	v_lshl_add_u64 v[4:5], v[40:41], 0, s[14:15]
	v_lshl_add_u64 v[6:7], v[42:43], 0, s[16:17]
	s_lshl_b64 s[16:17], s[0:1], 12
	v_lshl_add_u64 v[66:67], v[44:45], 0, s[14:15]
	s_lshl_b64 s[14:15], s[18:19], 12
	s_add_u32 s5, s2, s14
	s_addc_u32 s19, s3, s15
	s_add_u32 s14, s5, 0x2000
	global_load_dwordx4 v[32:35], v[48:49], off
	global_load_dwordx2 v[86:87], v[4:5], off nt
	global_load_dwordx2 v[84:85], v[4:5], off offset:512 nt
	global_load_dwordx2 v[82:83], v[4:5], off offset:1024 nt
	global_load_dwordx2 v[80:81], v[4:5], off offset:1536 nt
	global_load_dwordx2 v[78:79], v[4:5], off offset:2048 nt
	global_load_dwordx2 v[76:77], v[4:5], off offset:2560 nt
	global_load_dwordx2 v[74:75], v[4:5], off offset:3072 nt
	global_load_dwordx2 v[72:73], v[4:5], off offset:3584 nt
	global_load_dwordx4 v[24:27], v[6:7], off nt
	global_load_dwordx4 v[16:19], v[6:7], off offset:1024 nt
	global_load_dwordx4 v[8:11], v[6:7], off offset:2048 nt
	global_load_dwordx4 v[0:3], v[6:7], off offset:3072 nt
	v_lshl_add_u64 v[36:37], v[42:43], 0, s[16:17]
	s_addc_u32 s15, s19, 0
	global_load_dwordx4 v[28:31], v[36:37], off nt
	global_load_dwordx4 v[20:23], v[36:37], off offset:1024 nt
	global_load_dwordx4 v[12:15], v[36:37], off offset:2048 nt
	global_load_dwordx4 v[4:7], v[36:37], off offset:3072 nt
	s_lshl_b64 s[0:1], s[0:1], 11
	global_load_dwordx4 v[36:39], v94, s[14:15]
	s_add_u32 s16, s5, 0x3000
	s_addc_u32 s17, s19, 0
	s_add_u32 s18, s5, 0x4000
	v_lshl_add_u64 v[68:69], v[44:45], 0, s[0:1]
	s_addc_u32 s19, s19, 0
	s_and_b32 s0, s21, 0x8000
	s_and_b32 s1, s9, 0xfffff000
	s_and_b32 s5, s4, 0xffe
	s_add_i32 s0, s0, s1
	s_or_b32 s0, s0, s5
	s_ashr_i32 s1, s0, 31
	s_lshl_b64 s[0:1], s[0:1], 11
	v_lshl_add_u64 v[70:71], v[46:47], 0, s[0:1]
	s_add_i32 s21, s21, s22
	s_add_i32 s4, s4, s23
	s_waitcnt vmcnt(16)
	v_lshlrev_b32_e32 v98, 16, v86
	v_and_b32_e32 v99, 0xffff0000, v86
	v_lshlrev_b32_e32 v86, 16, v87
	v_and_b32_e32 v87, 0xffff0000, v87
	s_waitcnt vmcnt(15)
	v_lshlrev_b32_e32 v101, 16, v85
	v_lshlrev_b32_e32 v100, 16, v84
	v_and_b32_e32 v85, 0xffff0000, v85
	v_and_b32_e32 v84, 0xffff0000, v84
	s_waitcnt vmcnt(12)
	v_lshlrev_b32_e32 v108, 16, v78
	v_and_b32_e32 v109, 0xffff0000, v78
	v_lshlrev_b32_e32 v78, 16, v79
	v_and_b32_e32 v79, 0xffff0000, v79
	s_waitcnt vmcnt(11)
	v_lshlrev_b32_e32 v111, 16, v77
	v_lshlrev_b32_e32 v110, 16, v76
	v_and_b32_e32 v77, 0xffff0000, v77
	v_and_b32_e32 v76, 0xffff0000, v76
	v_lshlrev_b32_e32 v102, 16, v82
	v_and_b32_e32 v103, 0xffff0000, v82
	v_lshlrev_b32_e32 v82, 16, v83
	v_and_b32_e32 v83, 0xffff0000, v83
	v_lshlrev_b32_e32 v105, 16, v80
	s_waitcnt vmcnt(9)
	v_lshlrev_b32_e32 v115, 16, v72
	v_mul_f32_e32 v104, v87, v87
	v_pk_mul_f32 v[118:119], v[84:85], v[84:85]
	v_mul_f32_e32 v114, v99, v99
	v_mul_f32_e32 v124, v79, v79
	v_pk_mul_f32 v[126:127], v[76:77], v[76:77]
	v_mul_f32_e32 v128, v109, v109
	v_and_b32_e32 v107, 0xffff0000, v80
	v_lshlrev_b32_e32 v112, 16, v74
	v_and_b32_e32 v113, 0xffff0000, v74
	v_lshlrev_b32_e32 v74, 16, v75
	v_and_b32_e32 v75, 0xffff0000, v75
	v_mov_b32_e32 v121, v105
	v_mul_f32_e32 v120, v103, v103
	v_mul_f32_e32 v122, v83, v83
	v_mov_b32_e32 v123, v115
	v_mov_b32_e32 v134, v100
	v_mov_b32_e32 v135, v84
	v_mov_b32_e32 v84, v101
	v_mov_b32_e32 v136, v110
	v_mov_b32_e32 v137, v76
	v_mov_b32_e32 v76, v111
	v_pk_fma_f32 v[140:141], v[86:87], v[86:87], v[104:105] op_sel_hi:[1,1,0]
	v_pk_fma_f32 v[100:101], v[100:101], v[100:101], v[118:119]
	v_pk_fma_f32 v[118:119], v[98:99], v[98:99], v[114:115] op_sel_hi:[1,1,0]
	v_pk_fma_f32 v[124:125], v[78:79], v[78:79], v[124:125] op_sel_hi:[1,1,0]
	v_pk_fma_f32 v[110:111], v[110:111], v[110:111], v[126:127]
	v_pk_fma_f32 v[126:127], v[108:109], v[108:109], v[128:129] op_sel_hi:[1,1,0]
	v_lshlrev_b32_e32 v80, 16, v81
	v_and_b32_e32 v81, 0xffff0000, v81
	v_and_b32_e32 v117, 0xffff0000, v72
	v_lshlrev_b32_e32 v72, 16, v73
	v_and_b32_e32 v73, 0xffff0000, v73
	v_mul_f32_e32 v133, v107, v107
	v_mul_f32_e32 v130, v113, v113
	v_mul_f32_e32 v132, v75, v75
	v_pk_fma_f32 v[142:143], v[102:103], v[102:103], v[120:121] op_sel_hi:[1,1,0]
	v_pk_fma_f32 v[144:145], v[82:83], v[82:83], v[122:123] op_sel_hi:[1,1,0]
	v_mov_b32_e32 v104, v118
	v_mov_b32_e32 v120, v140
	v_mov_b32_e32 v114, v126
	v_mov_b32_e32 v122, v124
	v_mul_f32_e32 v139, v80, v80
	v_mul_f32_e32 v146, v81, v81
	v_mul_f32_e32 v147, v117, v117
	v_mul_f32_e32 v148, v72, v72
	v_mul_f32_e32 v149, v73, v73
	v_mov_b32_e32 v106, v105
	v_mov_b32_e32 v116, v115
	v_pk_fma_f32 v[128:129], v[112:113], v[112:113], v[130:131] op_sel_hi:[1,1,0]
	v_pk_fma_f32 v[130:131], v[74:75], v[74:75], v[132:133] op_sel_hi:[1,1,0]
	v_pk_add_f32 v[118:119], v[118:119], v[140:141]
	v_pk_add_f32 v[100:101], v[100:101], v[100:101] op_sel:[0,1] op_sel_hi:[1,0]
	v_pk_add_f32 v[124:125], v[126:127], v[124:125]
	v_pk_add_f32 v[110:111], v[110:111], v[110:111] op_sel:[0,1] op_sel_hi:[1,0]
	v_pk_mul_f32 v[104:105], v[104:105], v[120:121]
	v_pk_mul_f32 v[114:115], v[114:115], v[122:123]
	v_mov_b32_e32 v143, v139
	v_mov_b32_e32 v145, v146
	v_mov_b32_e32 v129, v148
	v_mov_b32_e32 v131, v149
	v_mov_b32_e32 v101, v133
	v_mov_b32_e32 v111, v147
	v_mov_b32_e32 v119, v105
	v_mov_b32_e32 v125, v115
	v_pk_add_f32 v[120:121], v[142:143], v[144:145]
	v_pk_add_f32 v[122:123], v[128:129], v[130:131]
	s_waitcnt vmcnt(0)
	v_pk_mul_f32 v[34:35], v[38:39], v[34:35]
	v_pk_mul_f32 v[32:33], v[36:37], v[32:33]
	v_pk_add_f32 v[36:37], v[118:119], v[100:101]
	v_pk_add_f32 v[38:39], v[124:125], v[110:111]
	v_pk_add_f32 v[36:37], v[36:37], v[120:121]
	v_pk_add_f32 v[38:39], v[38:39], v[122:123]
	v_mov_b32_e32 v101, v36
	v_mov_b32_e32 v100, v38
	v_mov_b32_e32 v36, v39
	v_pk_add_f32 v[36:37], v[100:101], v[36:37]
	ds_bpermute_b32 v39, v88, v37
	ds_bpermute_b32 v38, v88, v36
	s_waitcnt lgkmcnt(0)
	v_pk_add_f32 v[36:37], v[36:37], v[38:39]
	ds_bpermute_b32 v39, v89, v37
	ds_bpermute_b32 v38, v89, v36
	s_waitcnt lgkmcnt(0)
	v_pk_add_f32 v[36:37], v[36:37], v[38:39]
	ds_bpermute_b32 v39, v90, v37
	ds_bpermute_b32 v38, v90, v36
	s_waitcnt lgkmcnt(0)
	v_pk_add_f32 v[36:37], v[36:37], v[38:39]
	ds_bpermute_b32 v39, v91, v37
	ds_bpermute_b32 v38, v91, v36
	s_waitcnt lgkmcnt(0)
	v_pk_add_f32 v[36:37], v[36:37], v[38:39]
	ds_bpermute_b32 v39, v92, v37
	ds_bpermute_b32 v38, v92, v36
	s_waitcnt lgkmcnt(0)
	v_pk_add_f32 v[36:37], v[36:37], v[38:39]
	ds_bpermute_b32 v39, v93, v37
	ds_bpermute_b32 v38, v93, v36
	s_waitcnt lgkmcnt(0)
	v_pk_add_f32 v[36:37], v[36:37], v[38:39]
	s_nop 0
	v_pk_fma_f32 v[36:37], v[36:37], s[8:9], v[64:65] op_sel_hi:[1,0,0]
	s_nop 0
	v_mul_f32_e32 v38, 0x4b800000, v37
	v_cmp_gt_f32_e64 s[0:1], s24, v37
	v_mul_f32_e32 v39, 0x4b800000, v36
	v_cmp_gt_f32_e32 vcc, s24, v36
	v_cndmask_b32_e64 v37, v37, v38, s[0:1]
	v_rsq_f32_e32 v37, v37
	v_cndmask_b32_e32 v36, v36, v39, vcc
	v_rsq_f32_e32 v36, v36
	v_mul_f32_e32 v38, 0x45800000, v37
	v_cndmask_b32_e64 v37, v37, v38, s[0:1]
	v_mul_f32_e32 v39, 0x45800000, v36
	v_cndmask_b32_e32 v38, v36, v39, vcc
	v_mul_f32_e32 v36, 0.5, v37
	v_mul_f32_e32 v38, 0.5, v38
	v_pk_mul_f32 v[98:99], v[36:37], v[98:99] op_sel_hi:[0,1]
	v_pk_mul_f32 v[86:87], v[36:37], v[86:87] op_sel_hi:[0,1]
	v_pk_mul_f32 v[100:101], v[38:39], v[108:109] op_sel_hi:[0,1]
	v_pk_mul_f32 v[78:79], v[38:39], v[78:79] op_sel_hi:[0,1]
	v_pk_mul_f32 v[104:105], v[36:37], v[134:135] op_sel_hi:[0,1]
	v_pk_mul_f32 v[84:85], v[36:37], v[84:85] op_sel_hi:[0,1]
	v_pk_mul_f32 v[108:109], v[38:39], v[136:137] op_sel_hi:[0,1]
	v_pk_mul_f32 v[76:77], v[38:39], v[76:77] op_sel_hi:[0,1]
	v_pk_mul_f32 v[102:103], v[36:37], v[102:103] op_sel_hi:[0,1]
	v_pk_mul_f32 v[82:83], v[36:37], v[82:83] op_sel_hi:[0,1]
	v_pk_mul_f32 v[110:111], v[38:39], v[112:113] op_sel_hi:[0,1]
	v_pk_mul_f32 v[74:75], v[38:39], v[74:75] op_sel_hi:[0,1]
	v_pk_mul_f32 v[106:107], v[36:37], v[106:107] op_sel_hi:[0,1]
	v_pk_mul_f32 v[36:37], v[36:37], v[80:81] op_sel_hi:[0,1]
	v_pk_mul_f32 v[80:81], v[38:39], v[116:117] op_sel_hi:[0,1]
	v_pk_mul_f32 v[38:39], v[38:39], v[72:73] op_sel_hi:[0,1]
	v_pk_fma_f32 v[72:73], v[34:35], v[86:87], v[26:27]
	v_pk_fma_f32 v[86:87], v[32:33], v[98:99], v[24:25]
	v_pk_fma_f32 v[34:35], v[34:35], v[78:79], v[30:31]
	v_pk_fma_f32 v[32:33], v[32:33], v[100:101], v[28:29]
	v_cvt_pk_bf16_f32 v24, v86, v87
	v_cvt_pk_bf16_f32 v25, v72, v73
	v_cvt_pk_bf16_f32 v26, v32, v33
	v_cvt_pk_bf16_f32 v27, v34, v35
	global_store_dwordx2 v[66:67], v[24:25], off
	global_store_dwordx2 v[68:69], v[26:27], off
	global_load_dwordx4 v[24:27], v95, s[14:15]
	s_nop 0
	global_load_dwordx4 v[28:31], v[50:51], off
	v_pk_mul_f32 v[78:79], v[72:73], v[72:73]
	v_pk_mul_f32 v[98:99], v[86:87], v[86:87]
	v_pk_mul_f32 v[100:101], v[34:35], v[34:35]
	s_waitcnt vmcnt(0)
	v_pk_mul_f32 v[26:27], v[26:27], v[30:31]
	v_pk_mul_f32 v[24:25], v[24:25], v[28:29]
	v_pk_fma_f32 v[28:29], v[26:27], v[84:85], v[18:19]
	v_pk_fma_f32 v[30:31], v[24:25], v[104:105], v[16:17]
	v_pk_fma_f32 v[26:27], v[26:27], v[76:77], v[22:23]
	v_pk_fma_f32 v[24:25], v[24:25], v[108:109], v[20:21]
	v_cvt_pk_bf16_f32 v16, v30, v31
	v_cvt_pk_bf16_f32 v17, v28, v29
	v_cvt_pk_bf16_f32 v18, v24, v25
	v_cvt_pk_bf16_f32 v19, v26, v27
	global_store_dwordx2 v[66:67], v[16:17], off offset:512
	global_store_dwordx2 v[68:69], v[18:19], off offset:512
	global_load_dwordx4 v[16:19], v96, s[14:15]
	s_nop 0
	global_load_dwordx4 v[20:23], v[52:53], off
	v_pk_mul_f32 v[76:77], v[32:33], v[32:33]
	v_pk_mov_b32 v[84:85], v[98:99], v[78:79] op_sel:[1,0]
	v_mov_b32_e32 v99, v79
	v_pk_mov_b32 v[78:79], v[76:77], v[100:101] op_sel:[1,0]
	v_mov_b32_e32 v77, v101
	v_pk_add_f32 v[84:85], v[84:85], v[98:99]
	v_pk_add_f32 v[76:77], v[78:79], v[76:77]
	v_pk_add_f32 v[78:79], v[84:85], v[84:85] op_sel:[0,1] op_sel_hi:[1,0]
	v_pk_mul_f32 v[84:85], v[30:31], v[30:31]
	v_pk_mul_f32 v[98:99], v[26:27], v[26:27]
	v_pk_add_f32 v[76:77], v[76:77], v[76:77] op_sel:[0,1] op_sel_hi:[1,0]
	s_waitcnt vmcnt(0)
	v_pk_mul_f32 v[18:19], v[18:19], v[22:23]
	v_pk_mul_f32 v[16:17], v[16:17], v[20:21]
	v_pk_fma_f32 v[20:21], v[82:83], v[18:19], v[10:11]
	v_pk_fma_f32 v[22:23], v[102:103], v[16:17], v[8:9]
	v_pk_fma_f32 v[18:19], v[18:19], v[74:75], v[14:15]
	v_pk_fma_f32 v[16:17], v[16:17], v[110:111], v[12:13]
	v_cvt_pk_bf16_f32 v8, v22, v23
	v_cvt_pk_bf16_f32 v9, v20, v21
	v_cvt_pk_bf16_f32 v10, v16, v17
	v_cvt_pk_bf16_f32 v11, v18, v19
	global_store_dwordx2 v[66:67], v[8:9], off offset:1024
	global_store_dwordx2 v[68:69], v[10:11], off offset:1024
	global_load_dwordx4 v[8:11], v97, s[14:15]
	s_nop 0
	global_load_dwordx4 v[12:15], v[54:55], off
	v_pk_mul_f32 v[74:75], v[28:29], v[28:29]
	v_pk_mul_f32 v[82:83], v[24:25], v[24:25]
	v_pk_mov_b32 v[100:101], v[84:85], v[74:75] op_sel:[1,0]
	v_mov_b32_e32 v85, v75
	v_pk_mov_b32 v[74:75], v[82:83], v[98:99] op_sel:[1,0]
	v_mov_b32_e32 v83, v99
	v_pk_add_f32 v[84:85], v[100:101], v[84:85]
	v_pk_add_f32 v[74:75], v[74:75], v[82:83]
	v_pk_add_f32 v[82:83], v[84:85], v[84:85] op_sel:[0,1] op_sel_hi:[1,0]
	v_mul_f32_e32 v84, v23, v23
	v_mul_f32_e32 v98, v21, v21
	v_mul_f32_e32 v100, v17, v17
	v_mul_f32_e32 v102, v19, v19
	v_pk_add_f32 v[74:75], v[74:75], v[74:75] op_sel:[0,1] op_sel_hi:[1,0]
	v_pk_fma_f32 v[84:85], v[22:23], v[22:23], v[84:85] op_sel_hi:[1,1,0]
	v_pk_fma_f32 v[98:99], v[20:21], v[20:21], v[98:99] op_sel_hi:[1,1,0]
	v_pk_fma_f32 v[100:101], v[16:17], v[16:17], v[100:101] op_sel_hi:[1,1,0]
	v_pk_fma_f32 v[102:103], v[18:19], v[18:19], v[102:103] op_sel_hi:[1,1,0]
	s_waitcnt vmcnt(0)
	v_pk_mul_f32 v[10:11], v[10:11], v[14:15]
	v_pk_mul_f32 v[8:9], v[8:9], v[12:13]
	v_pk_fma_f32 v[12:13], v[36:37], v[10:11], v[2:3]
	v_pk_fma_f32 v[14:15], v[106:107], v[8:9], v[0:1]
	v_pk_fma_f32 v[36:37], v[38:39], v[10:11], v[6:7]
	v_pk_fma_f32 v[38:39], v[80:81], v[8:9], v[4:5]
	v_cvt_pk_bf16_f32 v0, v14, v15
	v_cvt_pk_bf16_f32 v1, v12, v13
	v_cvt_pk_bf16_f32 v2, v38, v39
	v_cvt_pk_bf16_f32 v3, v36, v37
	global_store_dwordx2 v[66:67], v[0:1], off offset:1536
	global_store_dwordx2 v[68:69], v[2:3], off offset:1536
	global_load_dwordx4 v[0:3], v94, s[18:19]
	s_nop 0
	global_load_dwordx4 v[4:7], v[56:57], off
	global_load_dwordx4 v[8:11], v94, s[16:17]
	v_mul_f32_e32 v79, v14, v14
	v_mul_f32_e32 v83, v15, v15
	v_mul_f32_e32 v85, v12, v12
	v_mul_f32_e32 v99, v13, v13
	v_mul_f32_e32 v101, v38, v38
	v_mul_f32_e32 v103, v39, v39
	v_mul_f32_e32 v77, v36, v36
	v_mul_f32_e32 v75, v37, v37
	v_pk_add_f32 v[66:67], v[78:79], v[82:83]
	v_pk_add_f32 v[68:69], v[84:85], v[98:99]
	v_pk_add_f32 v[78:79], v[100:101], v[102:103]
	v_pk_add_f32 v[74:75], v[76:77], v[74:75]
	v_pk_add_f32 v[66:67], v[66:67], v[68:69]
	v_pk_add_f32 v[68:69], v[78:79], v[74:75]
	v_mov_b32_e32 v75, v66
	v_mov_b32_e32 v74, v68
	v_mov_b32_e32 v66, v69
	v_pk_add_f32 v[66:67], v[74:75], v[66:67]
	ds_bpermute_b32 v69, v88, v67
	ds_bpermute_b32 v68, v88, v66
	s_waitcnt lgkmcnt(0)
	v_pk_add_f32 v[66:67], v[66:67], v[68:69]
	ds_bpermute_b32 v69, v89, v67
	ds_bpermute_b32 v68, v89, v66
	s_waitcnt lgkmcnt(0)
	v_pk_add_f32 v[66:67], v[66:67], v[68:69]
	ds_bpermute_b32 v69, v90, v67
	ds_bpermute_b32 v68, v90, v66
	s_waitcnt lgkmcnt(0)
	v_pk_add_f32 v[66:67], v[66:67], v[68:69]
	ds_bpermute_b32 v69, v91, v67
	ds_bpermute_b32 v68, v91, v66
	s_waitcnt lgkmcnt(0)
	v_pk_add_f32 v[66:67], v[66:67], v[68:69]
	ds_bpermute_b32 v69, v92, v67
	ds_bpermute_b32 v68, v92, v66
	s_waitcnt lgkmcnt(0)
	v_pk_add_f32 v[66:67], v[66:67], v[68:69]
	ds_bpermute_b32 v69, v93, v67
	ds_bpermute_b32 v68, v93, v66
	s_waitcnt lgkmcnt(0)
	v_pk_add_f32 v[66:67], v[66:67], v[68:69]
	s_nop 0
	v_pk_fma_f32 v[66:67], v[66:67], s[8:9], v[64:65] op_sel_hi:[1,0,0]
	s_add_i32 s9, s9, s20
	v_mul_f32_e32 v68, 0x4b800000, v67
	v_cmp_gt_f32_e64 s[0:1], s24, v67
	v_mul_f32_e32 v69, 0x4b800000, v66
	v_cmp_gt_f32_e32 vcc, s24, v66
	v_cndmask_b32_e64 v67, v67, v68, s[0:1]
	v_rsq_f32_e32 v67, v67
	v_cndmask_b32_e32 v66, v66, v69, vcc
	v_rsq_f32_e32 v68, v66
	s_cmp_lt_i32 s9, 0x8000
	v_mul_f32_e32 v66, 0x45800000, v67
	v_cndmask_b32_e64 v66, v67, v66, s[0:1]
	v_mul_f32_e32 v69, 0x45800000, v68
	v_cndmask_b32_e32 v68, v68, v69, vcc
	v_pk_mul_f32 v[74:75], v[86:87], v[66:67] op_sel_hi:[1,0]
	v_pk_mul_f32 v[72:73], v[72:73], v[66:67] op_sel_hi:[1,0]
	s_waitcnt vmcnt(2)
	v_pk_add_f32 v[2:3], v[2:3], 1.0 op_sel_hi:[1,0]
	v_pk_add_f32 v[0:1], v[0:1], 1.0 op_sel_hi:[1,0]
	s_waitcnt vmcnt(1)
	v_pk_mul_f32 v[2:3], v[6:7], v[2:3]
	v_pk_mul_f32 v[0:1], v[4:5], v[0:1]
	v_pk_mul_f32 v[32:33], v[32:33], v[68:69] op_sel_hi:[1,0]
	v_pk_mul_f32 v[34:35], v[34:35], v[68:69] op_sel_hi:[1,0]
	s_waitcnt vmcnt(0)
	v_pk_fma_f32 v[4:5], v[2:3], v[72:73], v[10:11]
	v_pk_fma_f32 v[6:7], v[0:1], v[74:75], v[8:9]
	v_pk_fma_f32 v[2:3], v[2:3], v[34:35], v[10:11]
	v_pk_fma_f32 v[0:1], v[0:1], v[32:33], v[8:9]
	v_cvt_pk_bf16_f32 v6, v6, v7
	v_cvt_pk_bf16_f32 v7, v4, v5
	v_cvt_pk_bf16_f32 v0, v0, v1
	v_cvt_pk_bf16_f32 v1, v2, v3
	global_store_dwordx2 v[70:71], v[6:7], off
	global_store_dwordx2 v[70:71], v[0:1], off offset:2048
	global_load_dwordx4 v[0:3], v95, s[18:19]
	s_nop 0
	global_load_dwordx4 v[4:7], v[58:59], off
	global_load_dwordx4 v[8:11], v95, s[16:17]
	v_pk_mul_f32 v[30:31], v[30:31], v[66:67] op_sel_hi:[1,0]
	v_pk_mul_f32 v[28:29], v[28:29], v[66:67] op_sel_hi:[1,0]
	v_pk_mul_f32 v[24:25], v[24:25], v[68:69] op_sel_hi:[1,0]
	v_pk_mul_f32 v[26:27], v[26:27], v[68:69] op_sel_hi:[1,0]
	v_pk_mul_f32 v[22:23], v[22:23], v[66:67] op_sel_hi:[1,0]
	v_pk_mul_f32 v[20:21], v[20:21], v[66:67] op_sel_hi:[1,0]
	v_pk_mul_f32 v[16:17], v[16:17], v[68:69] op_sel_hi:[1,0]
	v_pk_mul_f32 v[18:19], v[18:19], v[68:69] op_sel_hi:[1,0]
	v_pk_mul_f32 v[14:15], v[14:15], v[66:67] op_sel_hi:[1,0]
	v_pk_mul_f32 v[12:13], v[12:13], v[66:67] op_sel_hi:[1,0]
	s_waitcnt vmcnt(2)
	v_pk_add_f32 v[2:3], v[2:3], 1.0 op_sel_hi:[1,0]
	v_pk_add_f32 v[0:1], v[0:1], 1.0 op_sel_hi:[1,0]
	s_waitcnt vmcnt(1)
	v_pk_mul_f32 v[2:3], v[6:7], v[2:3]
	v_pk_mul_f32 v[0:1], v[4:5], v[0:1]
	s_waitcnt vmcnt(0)
	v_pk_fma_f32 v[4:5], v[2:3], v[28:29], v[10:11]
	v_pk_fma_f32 v[6:7], v[0:1], v[30:31], v[8:9]
	v_pk_fma_f32 v[2:3], v[2:3], v[26:27], v[10:11]
	v_pk_fma_f32 v[0:1], v[0:1], v[24:25], v[8:9]
	v_cvt_pk_bf16_f32 v6, v6, v7
	v_cvt_pk_bf16_f32 v7, v4, v5
	v_cvt_pk_bf16_f32 v0, v0, v1
	v_cvt_pk_bf16_f32 v1, v2, v3
	global_store_dwordx2 v[70:71], v[6:7], off offset:512
	global_store_dwordx2 v[70:71], v[0:1], off offset:2560
	global_load_dwordx4 v[0:3], v96, s[18:19]
	s_nop 0
	global_load_dwordx4 v[4:7], v[60:61], off
	global_load_dwordx4 v[8:11], v96, s[16:17]
	s_waitcnt vmcnt(2)
	v_pk_add_f32 v[2:3], v[2:3], 1.0 op_sel_hi:[1,0]
	v_pk_add_f32 v[0:1], v[0:1], 1.0 op_sel_hi:[1,0]
	s_waitcnt vmcnt(1)
	v_pk_mul_f32 v[2:3], v[6:7], v[2:3]
	v_pk_mul_f32 v[0:1], v[4:5], v[0:1]
	s_waitcnt vmcnt(0)
	v_pk_fma_f32 v[4:5], v[20:21], v[2:3], v[10:11]
	v_pk_fma_f32 v[6:7], v[22:23], v[0:1], v[8:9]
	v_pk_fma_f32 v[2:3], v[18:19], v[2:3], v[10:11]
	v_pk_fma_f32 v[0:1], v[16:17], v[0:1], v[8:9]
	v_cvt_pk_bf16_f32 v6, v6, v7
	v_cvt_pk_bf16_f32 v7, v4, v5
	v_cvt_pk_bf16_f32 v0, v0, v1
	v_cvt_pk_bf16_f32 v1, v2, v3
	global_store_dwordx2 v[70:71], v[6:7], off offset:1024
	global_store_dwordx2 v[70:71], v[0:1], off offset:3072
	global_load_dwordx4 v[0:3], v97, s[18:19]
	s_nop 0
	global_load_dwordx4 v[4:7], v[62:63], off
	global_load_dwordx4 v[8:11], v97, s[16:17]
	v_pk_mul_f32 v[16:17], v[38:39], v[68:69] op_sel_hi:[1,0]
	v_pk_mul_f32 v[18:19], v[36:37], v[68:69] op_sel_hi:[1,0]
	s_waitcnt vmcnt(2)
	v_pk_add_f32 v[2:3], v[2:3], 1.0 op_sel_hi:[1,0]
	v_pk_add_f32 v[0:1], v[0:1], 1.0 op_sel_hi:[1,0]
	s_waitcnt vmcnt(1)
	v_pk_mul_f32 v[2:3], v[6:7], v[2:3]
	v_pk_mul_f32 v[0:1], v[4:5], v[0:1]
	s_waitcnt vmcnt(0)
	v_pk_fma_f32 v[4:5], v[12:13], v[2:3], v[10:11]
	v_pk_fma_f32 v[6:7], v[14:15], v[0:1], v[8:9]
	v_pk_fma_f32 v[2:3], v[18:19], v[2:3], v[10:11]
	v_pk_fma_f32 v[0:1], v[16:17], v[0:1], v[8:9]
	v_cvt_pk_bf16_f32 v6, v6, v7
	v_cvt_pk_bf16_f32 v7, v4, v5
	v_cvt_pk_bf16_f32 v0, v0, v1
	v_cvt_pk_bf16_f32 v1, v2, v3
	global_store_dwordx2 v[70:71], v[6:7], off offset:1536
	global_store_dwordx2 v[70:71], v[0:1], off offset:3584
	s_cbranch_scc1 .LBB0_316
